# packed-FMA exponent arguments in the chunk-output key blocks; phase-3 state MFMAs fed by prefetched LDS fragments
# speedup vs baseline: 1.1525x; 1.0011x over previous
.LBB0_544:
	v_lshl_or_b32 v64, s0, 7, v147
	v_lshlrev_b32_e32 v251, 2, v64
	v_add_u32_e32 v64, s73, v251
	s_mul_i32 s1, s0, 0x2400
	ds_read_b32 v252, v64
	v_add_u32_e32 v64, s60, v251
	v_add_u32_e32 v156, s1, v160
	ds_read_b32 v146, v64
	ds_read_b128 v[80:83], v156 offset:58880
	ds_read_b128 v[64:67], v156 offset:54272
	ds_read_b128 v[148:151], v156 offset:54304
	ds_read_b128 v[152:155], v156 offset:58912
	s_waitcnt lgkmcnt(2)
	v_mfma_f32_32x32x16_bf16 v[64:79], v[64:67], v[96:99], 0
	s_lshl_b32 s0, s0, 9
	s_add_i32 s14, s57, s0
	s_or_b64 s[0:1], s[52:53], s[8:9]
	v_mov_b32_e32 v240, v147
	s_andn2_b64 vcc, exec, s[0:1]
	v_mfma_f32_32x32x16_bf16 v[80:95], v[80:83], v[96:99], 0
	s_waitcnt lgkmcnt(1)
	v_mfma_f32_32x32x16_bf16 v[64:79], v[148:151], v[100:103], v[64:79]
	s_waitcnt lgkmcnt(0)
	v_mfma_f32_32x32x16_bf16 v[80:95], v[152:155], v[100:103], v[80:95]
	ds_read_b128 v[148:151], v156 offset:54336
	ds_read_b128 v[152:155], v156 offset:58944
	s_waitcnt lgkmcnt(1)
	v_mfma_f32_32x32x16_bf16 v[64:79], v[148:151], v[104:107], v[64:79]
	s_waitcnt lgkmcnt(0)
	v_mfma_f32_32x32x16_bf16 v[80:95], v[152:155], v[104:107], v[80:95]
	ds_read_b128 v[148:151], v156 offset:54368
	ds_read_b128 v[152:155], v156 offset:58976
	s_waitcnt lgkmcnt(1)
	v_mfma_f32_32x32x16_bf16 v[64:79], v[148:151], v[108:111], v[64:79]
	s_waitcnt lgkmcnt(0)
	v_mfma_f32_32x32x16_bf16 v[80:95], v[152:155], v[108:111], v[80:95]
	s_nop 9
	v_mul_f32_e32 v252, s56, v252
	v_mul_f32_e64 v64, v146, v64
	v_mul_f32_e64 v65, v146, v65
	v_mul_f32_e64 v78, v146, v78
	v_mul_f32_e64 v79, v146, v79
	v_mul_f32_e64 v76, v146, v76
	v_mul_f32_e64 v77, v146, v77
	v_pk_mul_f32 v[74:75], v[146:147], v[74:75] op_sel_hi:[0,1]
	v_pk_mul_f32 v[72:73], v[146:147], v[72:73] op_sel_hi:[0,1]
	v_pk_mul_f32 v[70:71], v[146:147], v[70:71] op_sel_hi:[0,1]
	v_pk_mul_f32 v[68:69], v[146:147], v[68:69] op_sel_hi:[0,1]
	v_pk_mul_f32 v[66:67], v[146:147], v[66:67] op_sel_hi:[0,1]
	v_pk_mul_f32 v[80:81], v[146:147], v[80:81] op_sel_hi:[0,1]
	v_pk_mul_f32 v[94:95], v[146:147], v[94:95] op_sel_hi:[0,1]
	v_pk_mul_f32 v[92:93], v[146:147], v[92:93] op_sel_hi:[0,1]
	v_pk_mul_f32 v[90:91], v[146:147], v[90:91] op_sel_hi:[0,1]
	v_pk_mul_f32 v[88:89], v[146:147], v[88:89] op_sel_hi:[0,1]
	v_pk_mul_f32 v[86:87], v[146:147], v[86:87] op_sel_hi:[0,1]
	v_pk_mul_f32 v[84:85], v[146:147], v[84:85] op_sel_hi:[0,1]
	v_pk_mul_f32 v[82:83], v[146:147], v[82:83] op_sel_hi:[0,1]
	s_cbranch_vccnz .LBB0_582
	s_andn2_b64 vcc, exec, s[2:3]
	s_mov_b64 s[10:11], -1
	v_lshl_add_u32 v164, v168, 2, s14
	ds_read_b128 v[148:151], v164
	ds_read_b128 v[152:155], v164 offset:32
	ds_read_b128 v[156:159], v164 offset:64
	ds_read_b128 v[164:167], v164 offset:96
	s_waitcnt lgkmcnt(3)
	v_pk_fma_f32 v[148:149], v[148:149], s[56:57], v[252:253] op_sel_hi:[1,0,0]
	v_pk_fma_f32 v[150:151], v[150:151], s[56:57], v[252:253] op_sel_hi:[1,0,0]
	s_waitcnt lgkmcnt(2)
	v_pk_fma_f32 v[152:153], v[152:153], s[56:57], v[252:253] op_sel_hi:[1,0,0]
	v_pk_fma_f32 v[154:155], v[154:155], s[56:57], v[252:253] op_sel_hi:[1,0,0]
	s_waitcnt lgkmcnt(1)
	v_pk_fma_f32 v[156:157], v[156:157], s[56:57], v[252:253] op_sel_hi:[1,0,0]
	v_pk_fma_f32 v[158:159], v[158:159], s[56:57], v[252:253] op_sel_hi:[1,0,0]
	s_waitcnt lgkmcnt(0)
	v_pk_fma_f32 v[164:165], v[164:165], s[56:57], v[252:253] op_sel_hi:[1,0,0]
	v_pk_fma_f32 v[166:167], v[166:167], s[56:57], v[252:253] op_sel_hi:[1,0,0]
	v_exp_f32_e32 v148, v148
	v_exp_f32_e32 v149, v149
	v_exp_f32_e32 v150, v150
	v_exp_f32_e32 v151, v151
	v_exp_f32_e32 v152, v152
	v_exp_f32_e32 v153, v153
	v_exp_f32_e32 v154, v154
	v_exp_f32_e32 v155, v155
	v_exp_f32_e32 v156, v156
	v_exp_f32_e32 v157, v157
	v_exp_f32_e32 v158, v158
	v_exp_f32_e32 v159, v159
	v_exp_f32_e32 v164, v164
	v_exp_f32_e32 v165, v165
	v_exp_f32_e32 v166, v166
	v_exp_f32_e32 v167, v167
	v_pk_mul_f32 v[148:149], v[0:1], v[148:149]
	v_pk_mul_f32 v[150:151], v[2:3], v[150:151]
	v_pk_mul_f32 v[152:153], v[4:5], v[152:153]
	v_pk_mul_f32 v[154:155], v[6:7], v[154:155]
	v_pk_mul_f32 v[156:157], v[8:9], v[156:157]
	v_pk_mul_f32 v[158:159], v[10:11], v[158:159]
	v_pk_mul_f32 v[164:165], v[12:13], v[164:165]
	v_pk_mul_f32 v[166:167], v[14:15], v[166:167]

.LBB0_583:
	v_cndmask_b32_e64 v148, 0, 1, s[92:93]
	v_cndmask_b32_e64 v149, 0, 1, s[52:53]
	v_cndmask_b32_e64 v148, v148, v149, s[8:9]
	v_and_b32_e32 v148, 1, v148
	v_cmp_eq_u32_e32 vcc, 1, v148
	s_xor_b64 s[10:11], s[8:9], -1
	s_cbranch_vccnz .LBB0_621
	v_readlane_b32 s0, v254, 10
	v_readlane_b32 s1, v254, 11
	s_andn2_b64 vcc, exec, s[0:1]
	s_mov_b64 s[12:13], -1
	v_lshl_add_u32 v164, v168, 2, s14
	ds_read_b128 v[148:151], v164 offset:128
	ds_read_b128 v[152:155], v164 offset:160
	ds_read_b128 v[156:159], v164 offset:192
	ds_read_b128 v[164:167], v164 offset:224
	s_waitcnt lgkmcnt(3)
	v_pk_fma_f32 v[148:149], v[148:149], s[56:57], v[252:253] op_sel_hi:[1,0,0]
	v_pk_fma_f32 v[150:151], v[150:151], s[56:57], v[252:253] op_sel_hi:[1,0,0]
	s_waitcnt lgkmcnt(2)
	v_pk_fma_f32 v[152:153], v[152:153], s[56:57], v[252:253] op_sel_hi:[1,0,0]
	v_pk_fma_f32 v[154:155], v[154:155], s[56:57], v[252:253] op_sel_hi:[1,0,0]
	s_waitcnt lgkmcnt(1)
	v_pk_fma_f32 v[156:157], v[156:157], s[56:57], v[252:253] op_sel_hi:[1,0,0]
	v_pk_fma_f32 v[158:159], v[158:159], s[56:57], v[252:253] op_sel_hi:[1,0,0]
	s_waitcnt lgkmcnt(0)
	v_pk_fma_f32 v[164:165], v[164:165], s[56:57], v[252:253] op_sel_hi:[1,0,0]
	v_pk_fma_f32 v[166:167], v[166:167], s[56:57], v[252:253] op_sel_hi:[1,0,0]
	v_exp_f32_e32 v148, v148
	v_exp_f32_e32 v149, v149
	v_exp_f32_e32 v150, v150
	v_exp_f32_e32 v151, v151
	v_exp_f32_e32 v152, v152
	v_exp_f32_e32 v153, v153
	v_exp_f32_e32 v154, v154
	v_exp_f32_e32 v155, v155
	v_exp_f32_e32 v156, v156
	v_exp_f32_e32 v157, v157
	v_exp_f32_e32 v158, v158
	v_exp_f32_e32 v159, v159
	v_exp_f32_e32 v164, v164
	v_exp_f32_e32 v165, v165
	v_exp_f32_e32 v166, v166
	v_exp_f32_e32 v167, v167
	v_pk_mul_f32 v[148:149], v[16:17], v[148:149]
	v_pk_mul_f32 v[150:151], v[18:19], v[150:151]
	v_pk_mul_f32 v[152:153], v[20:21], v[152:153]
	v_pk_mul_f32 v[154:155], v[22:23], v[154:155]
	v_pk_mul_f32 v[156:157], v[24:25], v[156:157]
	v_pk_mul_f32 v[158:159], v[26:27], v[158:159]
	v_pk_mul_f32 v[164:165], v[28:29], v[164:165]
	v_pk_mul_f32 v[166:167], v[30:31], v[166:167]

.LBB0_621:
	v_cndmask_b32_e64 v148, 0, 1, s[76:77]
	v_cndmask_b32_e64 v149, 0, 1, s[80:81]
	v_cndmask_b32_e64 v148, v148, v149, s[8:9]
	v_and_b32_e32 v148, 1, v148
	v_cmp_eq_u32_e32 vcc, 1, v148
	s_cbranch_vccnz .LBB0_660
	v_readlane_b32 s0, v254, 12
	v_readlane_b32 s1, v254, 13
	s_andn2_b64 vcc, exec, s[0:1]
	s_mov_b64 s[12:13], -1
	v_lshl_add_u32 v164, v168, 2, s14
	ds_read_b128 v[148:151], v164 offset:256
	ds_read_b128 v[152:155], v164 offset:288
	ds_read_b128 v[156:159], v164 offset:320
	ds_read_b128 v[164:167], v164 offset:352
	s_waitcnt lgkmcnt(3)
	v_pk_fma_f32 v[148:149], v[148:149], s[56:57], v[252:253] op_sel_hi:[1,0,0]
	v_pk_fma_f32 v[150:151], v[150:151], s[56:57], v[252:253] op_sel_hi:[1,0,0]
	s_waitcnt lgkmcnt(2)
	v_pk_fma_f32 v[152:153], v[152:153], s[56:57], v[252:253] op_sel_hi:[1,0,0]
	v_pk_fma_f32 v[154:155], v[154:155], s[56:57], v[252:253] op_sel_hi:[1,0,0]
	s_waitcnt lgkmcnt(1)
	v_pk_fma_f32 v[156:157], v[156:157], s[56:57], v[252:253] op_sel_hi:[1,0,0]
	v_pk_fma_f32 v[158:159], v[158:159], s[56:57], v[252:253] op_sel_hi:[1,0,0]
	s_waitcnt lgkmcnt(0)
	v_pk_fma_f32 v[164:165], v[164:165], s[56:57], v[252:253] op_sel_hi:[1,0,0]
	v_pk_fma_f32 v[166:167], v[166:167], s[56:57], v[252:253] op_sel_hi:[1,0,0]
	v_exp_f32_e32 v148, v148
	v_exp_f32_e32 v149, v149
	v_exp_f32_e32 v150, v150
	v_exp_f32_e32 v151, v151
	v_exp_f32_e32 v152, v152
	v_exp_f32_e32 v153, v153
	v_exp_f32_e32 v154, v154
	v_exp_f32_e32 v155, v155
	v_exp_f32_e32 v156, v156
	v_exp_f32_e32 v157, v157
	v_exp_f32_e32 v158, v158
	v_exp_f32_e32 v159, v159
	v_exp_f32_e32 v164, v164
	v_exp_f32_e32 v165, v165
	v_exp_f32_e32 v166, v166
	v_exp_f32_e32 v167, v167
	v_pk_mul_f32 v[148:149], v[32:33], v[148:149]
	v_pk_mul_f32 v[150:151], v[34:35], v[150:151]
	v_pk_mul_f32 v[152:153], v[36:37], v[152:153]
	v_pk_mul_f32 v[154:155], v[38:39], v[154:155]
	v_pk_mul_f32 v[156:157], v[40:41], v[156:157]
	v_pk_mul_f32 v[158:159], v[42:43], v[158:159]
	v_pk_mul_f32 v[164:165], v[44:45], v[164:165]
	v_pk_mul_f32 v[166:167], v[46:47], v[166:167]

.LBB0_661:
	s_mov_b64 s[12:13], -1
	s_andn2_b64 vcc, exec, s[62:63]
	v_lshl_add_u32 v239, v168, 2, s14
	ds_read_b128 v[148:151], v239 offset:384
	ds_read_b128 v[152:155], v239 offset:416
	ds_read_b128 v[156:159], v239 offset:448
	ds_read_b128 v[164:167], v239 offset:480
	s_waitcnt lgkmcnt(3)
	v_pk_fma_f32 v[148:149], v[148:149], s[56:57], v[252:253] op_sel_hi:[1,0,0]
	v_pk_fma_f32 v[150:151], v[150:151], s[56:57], v[252:253] op_sel_hi:[1,0,0]
	s_waitcnt lgkmcnt(2)
	v_pk_fma_f32 v[152:153], v[152:153], s[56:57], v[252:253] op_sel_hi:[1,0,0]
	v_pk_fma_f32 v[154:155], v[154:155], s[56:57], v[252:253] op_sel_hi:[1,0,0]
	s_waitcnt lgkmcnt(1)
	v_pk_fma_f32 v[156:157], v[156:157], s[56:57], v[252:253] op_sel_hi:[1,0,0]
	v_pk_fma_f32 v[158:159], v[158:159], s[56:57], v[252:253] op_sel_hi:[1,0,0]
	s_waitcnt lgkmcnt(0)
	v_pk_fma_f32 v[164:165], v[164:165], s[56:57], v[252:253] op_sel_hi:[1,0,0]
	v_pk_fma_f32 v[166:167], v[166:167], s[56:57], v[252:253] op_sel_hi:[1,0,0]
	v_exp_f32_e32 v148, v148
	v_exp_f32_e32 v149, v149
	v_exp_f32_e32 v150, v150
	v_exp_f32_e32 v151, v151
	v_exp_f32_e32 v152, v152
	v_exp_f32_e32 v153, v153
	v_exp_f32_e32 v154, v154
	v_exp_f32_e32 v155, v155
	v_exp_f32_e32 v156, v156
	v_exp_f32_e32 v157, v157
	v_exp_f32_e32 v158, v158
	v_exp_f32_e32 v159, v159
	v_exp_f32_e32 v164, v164
	v_exp_f32_e32 v165, v165
	v_exp_f32_e32 v166, v166
	v_exp_f32_e32 v167, v167
	v_pk_mul_f32 v[148:149], v[48:49], v[148:149]
	v_pk_mul_f32 v[150:151], v[50:51], v[150:151]
	v_pk_mul_f32 v[152:153], v[52:53], v[152:153]
	v_pk_mul_f32 v[154:155], v[54:55], v[154:155]
	v_pk_mul_f32 v[156:157], v[56:57], v[156:157]
	v_pk_mul_f32 v[158:159], v[58:59], v[158:159]
	v_pk_mul_f32 v[164:165], v[60:61], v[164:165]
	v_pk_mul_f32 v[166:167], v[62:63], v[166:167]

.Lkc3_st:
	global_store_dwordx4 v127, v[110:113], s[2:3]
	global_store_dwordx4 v127, v[114:117], s[2:3] offset:16
	global_store_dwordx4 v127, v[118:121], s[2:3] offset:32
	global_store_dwordx4 v127, v[122:125], s[2:3] offset:48
	v_lshl_add_u32 v34, v212, 2, s33
	ds_read2st64_b32 v[32:33], v34 offset0:204 offset1:206
	v_mul_u32_u24_e32 v36, 0x1100, v213
	v_or_b32_e32 v37, v36, v212
	v_lshl_add_u32 v37, v37, 1, s33
	v_lshlrev_b32_e32 v38, 1, v212
	s_waitcnt lgkmcnt(0)
	v_mul_f32_e32 v35, v32, v58
	v_cvt_pk_bf16_f32 v35, v35, s0
	ds_write_b16 v37, v35
	v_mul_f32_e32 v35, v58, v33
	v_sub_u32_e32 v34, v34, v38
	v_cvt_pk_bf16_f32 v35, v35, s0
	v_lshl_add_u32 v34, v36, 1, v34
	ds_write_b16 v34, v35 offset:17408
	v_mul_f32_e32 v35, v32, v59
	v_cvt_pk_bf16_f32 v35, v35, s0
	ds_write_b16 v34, v35 offset:272
	v_mul_f32_e32 v35, v59, v33
	v_cvt_pk_bf16_f32 v35, v35, s0
	ds_write_b16 v34, v35 offset:17680
	v_mul_f32_e32 v35, v32, v88
	v_cvt_pk_bf16_f32 v35, v35, s0
	ds_write_b16 v34, v35 offset:544
	v_mul_f32_e32 v35, v88, v33
	v_cvt_pk_bf16_f32 v35, v35, s0
	ds_write_b16 v34, v35 offset:17952
	v_mul_f32_e32 v35, v32, v89
	v_cvt_pk_bf16_f32 v35, v35, s0
	ds_write_b16 v34, v35 offset:816
	v_mul_f32_e32 v35, v89, v33
	v_cvt_pk_bf16_f32 v35, v35, s0
	ds_write_b16 v34, v35 offset:18224
	v_mul_f32_e32 v35, v32, v78
	v_cvt_pk_bf16_f32 v35, v35, s0
	ds_write_b16 v34, v35 offset:1088
	v_mul_f32_e32 v35, v78, v33
	v_cvt_pk_bf16_f32 v35, v35, s0
	ds_write_b16 v34, v35 offset:18496
	v_mul_f32_e32 v35, v32, v79
	v_cvt_pk_bf16_f32 v35, v35, s0
	ds_write_b16 v34, v35 offset:1360
	v_mul_f32_e32 v35, v79, v33
	v_cvt_pk_bf16_f32 v35, v35, s0
	ds_write_b16 v34, v35 offset:18768
	v_mul_f32_e32 v35, v32, v76
	v_cvt_pk_bf16_f32 v35, v35, s0
	ds_write_b16 v34, v35 offset:1632
	v_mul_f32_e32 v35, v76, v33
	v_cvt_pk_bf16_f32 v35, v35, s0
	ds_write_b16 v34, v35 offset:19040
	v_mul_f32_e32 v35, v32, v77
	v_cvt_pk_bf16_f32 v35, v35, s0
	ds_write_b16 v34, v35 offset:1904
	v_mul_f32_e32 v35, v77, v33
	v_cvt_pk_bf16_f32 v35, v35, s0
	ds_write_b16 v34, v35 offset:19312
	v_mul_f32_e32 v35, v32, v80
	v_cvt_pk_bf16_f32 v35, v35, s0
	ds_write_b16 v34, v35 offset:2176
	v_mul_f32_e32 v35, v80, v33
	v_cvt_pk_bf16_f32 v35, v35, s0
	ds_write_b16 v34, v35 offset:19584
	v_mul_f32_e32 v35, v32, v81
	v_cvt_pk_bf16_f32 v35, v35, s0
	ds_write_b16 v34, v35 offset:2448
	v_mul_f32_e32 v35, v81, v33
	v_cvt_pk_bf16_f32 v35, v35, s0
	ds_write_b16 v34, v35 offset:19856
	v_mul_f32_e32 v35, v32, v84
	v_cvt_pk_bf16_f32 v35, v35, s0
	ds_write_b16 v34, v35 offset:2720
	v_mul_f32_e32 v35, v84, v33
	v_cvt_pk_bf16_f32 v35, v35, s0
	ds_write_b16 v34, v35 offset:20128
	v_mul_f32_e32 v35, v32, v85
	v_cvt_pk_bf16_f32 v35, v35, s0
	ds_write_b16 v34, v35 offset:2992
	v_mul_f32_e32 v35, v85, v33
	v_cvt_pk_bf16_f32 v35, v35, s0
	ds_write_b16 v34, v35 offset:20400
	v_mul_f32_e32 v35, v32, v82
	v_cvt_pk_bf16_f32 v35, v35, s0
	ds_write_b16 v34, v35 offset:3264
	v_mul_f32_e32 v35, v82, v33
	v_cvt_pk_bf16_f32 v35, v35, s0
	ds_write_b16 v34, v35 offset:20672
	v_mul_f32_e32 v35, v32, v83
	v_cvt_pk_bf16_f32 v35, v35, s0
	ds_write_b16 v34, v35 offset:3536
	v_mul_f32_e32 v35, v83, v33
	v_cvt_pk_bf16_f32 v35, v35, s0
	ds_write_b16 v34, v35 offset:20944
	v_mul_f32_e32 v35, v32, v56
	v_cvt_pk_bf16_f32 v35, v35, s0
	ds_write_b16 v34, v35 offset:3808
	v_mul_f32_e32 v35, v56, v33
	v_cvt_pk_bf16_f32 v35, v35, s0
	ds_write_b16 v34, v35 offset:21216
	v_mul_f32_e32 v35, v32, v57
	v_cvt_pk_bf16_f32 v35, v35, s0
	ds_write_b16 v34, v35 offset:4080
	v_mul_f32_e32 v35, v57, v33
	v_cvt_pk_bf16_f32 v35, v35, s0
	ds_write_b16 v34, v35 offset:21488
	v_mul_f32_e32 v35, v32, v18
	v_mul_f32_e32 v18, v18, v33
	v_cvt_pk_bf16_f32 v18, v18, s0
	ds_write_b16 v34, v18 offset:21760
	v_mul_f32_e32 v18, v32, v19
	v_cvt_pk_bf16_f32 v18, v18, s0
	ds_write_b16 v34, v18 offset:4624
	v_mul_f32_e32 v18, v19, v33
	v_cvt_pk_bf16_f32 v18, v18, s0
	ds_write_b16 v34, v18 offset:22032
	v_mul_f32_e32 v18, v32, v26
	v_cvt_pk_bf16_f32 v18, v18, s0
	ds_write_b16 v34, v18 offset:4896
	v_mul_f32_e32 v18, v26, v33
	v_cvt_pk_bf16_f32 v18, v18, s0
	ds_write_b16 v34, v18 offset:22304
	v_mul_f32_e32 v18, v32, v27
	v_cvt_pk_bf16_f32 v18, v18, s0
	ds_write_b16 v34, v18 offset:5168
	v_mul_f32_e32 v18, v27, v33
	v_cvt_pk_bf16_f32 v18, v18, s0
	ds_write_b16 v34, v18 offset:22576
	v_mul_f32_e32 v18, v32, v24
	v_cvt_pk_bf16_f32 v18, v18, s0
	ds_write_b16 v34, v18 offset:5440
	v_mul_f32_e32 v18, v24, v33
	v_cvt_pk_bf16_f32 v18, v18, s0
	ds_write_b16 v34, v18 offset:22848
	v_mul_f32_e32 v18, v32, v25
	v_cvt_pk_bf16_f32 v18, v18, s0
	ds_write_b16 v34, v18 offset:5712
	v_mul_f32_e32 v18, v25, v33
	v_cvt_pk_bf16_f32 v18, v18, s0
	ds_write_b16 v34, v18 offset:23120
	v_mul_f32_e32 v18, v32, v16
	v_mul_f32_e32 v16, v16, v33
	v_cvt_pk_bf16_f32 v16, v16, s0
	ds_write_b16 v34, v16 offset:23392
	v_mul_f32_e32 v16, v32, v17
	v_cvt_pk_bf16_f32 v16, v16, s0
	ds_write_b16 v34, v16 offset:6256
	v_mul_f32_e32 v16, v17, v33
	v_cvt_pk_bf16_f32 v16, v16, s0
	ds_write_b16 v34, v16 offset:23664
	v_mul_f32_e32 v16, v32, v20
	v_cvt_pk_bf16_f32 v16, v16, s0
	ds_write_b16 v34, v16 offset:6528
	v_mul_f32_e32 v16, v20, v33
	v_cvt_pk_bf16_f32 v16, v16, s0
	ds_write_b16 v34, v16 offset:23936
	v_mul_f32_e32 v16, v32, v21
	v_cvt_pk_bf16_f32 v16, v16, s0
	ds_write_b16 v34, v16 offset:6800
	v_mul_f32_e32 v16, v21, v33
	v_cvt_pk_bf16_f32 v16, v16, s0
	ds_write_b16 v34, v16 offset:24208
	v_mul_f32_e32 v16, v32, v22
	v_cvt_pk_bf16_f32 v16, v16, s0
	ds_write_b16 v34, v16 offset:7072
	v_mul_f32_e32 v16, v22, v33
	v_cvt_pk_bf16_f32 v16, v16, s0
	ds_write_b16 v34, v16 offset:24480
	v_mul_f32_e32 v16, v32, v23
	v_cvt_pk_bf16_f32 v16, v16, s0
	ds_write_b16 v34, v16 offset:7344
	v_mul_f32_e32 v16, v23, v33
	v_cvt_pk_bf16_f32 v16, v16, s0
	ds_write_b16 v34, v16 offset:24752
	v_mul_f32_e32 v16, v32, v28
	v_cvt_pk_bf16_f32 v16, v16, s0
	ds_write_b16 v34, v16 offset:7616
	v_mul_f32_e32 v16, v28, v33
	v_cvt_pk_bf16_f32 v16, v16, s0
	ds_write_b16 v34, v16 offset:25024
	v_mul_f32_e32 v16, v32, v29
	v_cvt_pk_bf16_f32 v16, v16, s0
	ds_write_b16 v34, v16 offset:7888
	v_mul_f32_e32 v16, v29, v33
	v_cvt_pk_bf16_f32 v16, v16, s0
	ds_write_b16 v34, v16 offset:25296
	v_mul_f32_e32 v16, v32, v30
	v_cvt_pk_bf16_f32 v16, v16, s0
	ds_write_b16 v34, v16 offset:8160
	v_mul_f32_e32 v16, v30, v33
	v_mul_f32_e32 v31, 0x3e000000, v45
	v_cvt_pk_bf16_f32 v16, v16, s0
	ds_write_b16 v34, v16 offset:25568
	v_mul_f32_e32 v16, v31, v32
	v_cvt_pk_bf16_f32 v16, v16, s0
	ds_write_b16 v34, v16 offset:8432
	v_mul_f32_e32 v16, v31, v33
	v_cvt_pk_bf16_f32 v35, v35, s0
	v_cvt_pk_bf16_f32 v18, v18, s0
	v_cvt_pk_bf16_f32 v16, v16, s0
	ds_write_b16 v34, v35 offset:4352
	ds_write_b16 v34, v18 offset:5984
	ds_write_b16 v34, v16 offset:25840
	s_waitcnt vmcnt(4)
	ds_write_b16 v37, v12 offset:34816
	ds_write_b16_d16_hi v34, v12 offset:35088
	ds_write_b16 v34, v13 offset:35360
	ds_write_b16_d16_hi v34, v13 offset:35632
	ds_write_b16 v34, v14 offset:35904
	ds_write_b16_d16_hi v34, v14 offset:36176
	ds_write_b16 v34, v15 offset:36448
	ds_write_b16_d16_hi v34, v15 offset:36720
	ds_write_b16 v34, v8 offset:36992
	ds_write_b16_d16_hi v34, v8 offset:37264
	ds_write_b16 v34, v9 offset:37536
	ds_write_b16_d16_hi v34, v9 offset:37808
	ds_write_b16 v34, v10 offset:38080
	ds_write_b16_d16_hi v34, v10 offset:38352
	ds_write_b16 v34, v11 offset:38624
	ds_write_b16_d16_hi v34, v11 offset:38896
	ds_write_b16 v34, v4 offset:39168
	ds_write_b16_d16_hi v34, v4 offset:39440
	ds_write_b16 v34, v5 offset:39712
	ds_write_b16_d16_hi v34, v5 offset:39984
	ds_write_b16 v34, v6 offset:40256
	ds_write_b16_d16_hi v34, v6 offset:40528
	ds_write_b16 v34, v7 offset:40800
	ds_write_b16_d16_hi v34, v7 offset:41072
	ds_write_b16 v34, v0 offset:41344
	ds_write_b16_d16_hi v34, v0 offset:41616
	ds_write_b16 v34, v1 offset:41888
	ds_write_b16_d16_hi v34, v1 offset:42160
	ds_write_b16 v34, v2 offset:42432
	ds_write_b16_d16_hi v34, v2 offset:42704
	ds_write_b16 v34, v3 offset:42976
	ds_write_b16_d16_hi v34, v3 offset:43248
	v_lshrrev_b32_e32 v3, 2, v211
	v_bfe_u32 v0, v209, 6, 1
	v_and_b32_e32 v1, 31, v211
	v_and_b32_e32 v3, 32, v3
	v_or_b32_e32 v4, v3, v1
	v_lshl_or_b32 v5, v0, 5, v1
	v_lshlrev_b32_e32 v1, 7, v1
	v_lshl_or_b32 v160, v0, 12, v1
	s_bfe_u32 s1, s38, 0x10003
	v_lshrrev_b32_e32 v2, 5, v208
	v_lshl_add_u64 v[0:1], s[20:21], 0, v[160:161]
	v_lshlrev_b32_e32 v160, 1, v3
	s_and_b64 s[2:3], s[26:27], exec
	v_lshl_add_u64 v[0:1], v[0:1], 0, v[160:161]
	v_lshlrev_b32_e32 v160, 3, v2
	v_lshl_add_u64 v[24:25], v[0:1], 0, v[160:161]
	v_lshl_add_u32 v0, v2, 4, s33
	s_movk_i32 s2, 0x110
	v_mad_u32_u24 v54, v4, s2, v0
	s_waitcnt lgkmcnt(0)
	s_barrier
	v_mad_u32_u24 v55, v5, s2, v0
	ds_read_b128 v[60:63], v54
	ds_read_b128 v[26:29], v55 offset:34816
	ds_read_b128 v[64:67], v54 offset:32
	ds_read_b128 v[30:33], v55 offset:34848
	ds_read_b128 v[68:71], v54 offset:64
	ds_read_b128 v[34:37], v55 offset:34880
	ds_read_b128 v[72:75], v54 offset:96
	ds_read_b128 v[38:41], v55 offset:34912
	ds_read_b128 v[132:135], v54 offset:128
	ds_read_b128 v[42:45], v55 offset:34944
	ds_read_b128 v[136:139], v54 offset:160
	ds_read_b128 v[46:49], v55 offset:34976
	ds_read_b128 v[140:143], v54 offset:192
	ds_read_b128 v[20:23], v55 offset:35008
	ds_read_b128 v[144:147], v54 offset:224
	ds_read_b128 v[16:19], v55 offset:35040
	s_waitcnt lgkmcnt(14)
	v_mfma_f32_32x32x16_bf16 v[0:15], v[60:63], v[26:29], 0
	ds_read_b128 v[148:151], v54 offset:17408
	s_cselect_b32 s0, 0x43, 1
	s_lshl_b32 s2, s1, 5
	s_waitcnt lgkmcnt(13)
	v_mfma_f32_32x32x16_bf16 v[0:15], v[64:67], v[30:33], v[0:15]
	ds_read_b128 v[152:155], v54 offset:17440
	s_lshl_b32 s3, s36, 3
	s_add_i32 s2, s2, s3
	s_waitcnt lgkmcnt(12)
	v_mfma_f32_32x32x16_bf16 v[0:15], v[68:71], v[34:37], v[0:15]
	ds_read_b128 v[156:159], v54 offset:17472
	s_or_b32 s2, s2, s37
	s_sub_i32 s0, s0, s35
	s_waitcnt lgkmcnt(11)
	v_mfma_f32_32x32x16_bf16 v[0:15], v[72:75], v[38:41], v[0:15]
	ds_read_b128 v[164:167], v54 offset:17504
	s_mul_i32 s3, s2, 0x42
	s_ashr_i32 s6, s35, 31
	s_waitcnt lgkmcnt(10)
	v_mfma_f32_32x32x16_bf16 v[0:15], v[132:135], v[42:45], v[0:15]
	ds_read_b128 v[168:171], v54 offset:17536
	s_mul_hi_i32 s5, s2, 0x42
	s_add_u32 s4, s3, s35
	s_waitcnt lgkmcnt(9)
	v_mfma_f32_32x32x16_bf16 v[0:15], v[136:139], v[46:49], v[0:15]
	ds_read_b128 v[172:175], v54 offset:17568
	s_addc_u32 s5, s5, s6
	s_lshl_b64 s[4:5], s[4:5], 13
	s_waitcnt lgkmcnt(8)
	v_mfma_f32_32x32x16_bf16 v[0:15], v[140:143], v[20:23], v[0:15]
	ds_read_b128 v[200:203], v54 offset:17600
	s_add_i32 s2, s2, 16
	s_addk_i32 s3, 0x420
	s_waitcnt lgkmcnt(7)
	v_mfma_f32_32x32x16_bf16 v[0:15], v[144:147], v[16:19], v[0:15]
	ds_read_b128 v[204:207], v54 offset:17632
	v_lshl_add_u64 v[50:51], v[24:25], 0, s[4:5]
	s_mul_hi_i32 s4, s2, 0x42
	s_add_u32 s2, s3, s0
	s_addc_u32 s3, s4, 0
	s_lshl_b64 s[2:3], s[2:3], 13
	s_cmp_lg_u32 s1, 0
	s_movk_i32 s1, 0x80
	s_nop 4
	v_cvt_pk_bf16_f32 v0, v0, v1
	v_cvt_pk_bf16_f32 v1, v2, v3
	v_cvt_pk_bf16_f32 v2, v4, v5
	v_cvt_pk_bf16_f32 v3, v6, v7
	v_cvt_pk_bf16_f32 v4, v8, v9
	v_cvt_pk_bf16_f32 v5, v10, v11
	v_cvt_pk_bf16_f32 v6, v12, v13
	v_cvt_pk_bf16_f32 v7, v14, v15
	v_mbcnt_lo_u32_b32 v8, -1, 0
	v_mbcnt_hi_u32_b32 v8, -1, v8
	v_lshrrev_b32_e32 v8, 2, v8
	v_and_b32_e32 v8, 8, v8
	v_mov_b32_e32 v9, 0
	v_permlane32_swap_b32_e32 v0, v2
	v_permlane32_swap_b32_e32 v1, v3
	v_permlane32_swap_b32_e32 v4, v6
	v_permlane32_swap_b32_e32 v5, v7
	v_lshl_add_u64 v[50:51], v[50:51], 0, v[8:9]
	global_store_dwordx4 v[50:51], v[0:3], off
	global_store_dwordx4 v[50:51], v[4:7], off offset:32
	s_nop 1
	s_waitcnt lgkmcnt(7)
	v_mfma_f32_32x32x16_bf16 v[0:15], v[148:151], v[26:29], 0
	s_waitcnt lgkmcnt(6)
	v_mfma_f32_32x32x16_bf16 v[0:15], v[152:155], v[30:33], v[0:15]
	v_cmp_gt_u32_e32 vcc, s1, v209
	s_waitcnt lgkmcnt(5)
	v_mfma_f32_32x32x16_bf16 v[0:15], v[156:159], v[34:37], v[0:15]
	s_waitcnt lgkmcnt(4)
	v_mfma_f32_32x32x16_bf16 v[0:15], v[164:167], v[38:41], v[0:15]
	s_waitcnt lgkmcnt(3)
	v_mfma_f32_32x32x16_bf16 v[0:15], v[168:171], v[42:45], v[0:15]
	s_waitcnt lgkmcnt(2)
	v_mfma_f32_32x32x16_bf16 v[0:15], v[172:175], v[46:49], v[0:15]
	s_waitcnt lgkmcnt(1)
	v_mfma_f32_32x32x16_bf16 v[0:15], v[200:203], v[20:23], v[0:15]
	s_waitcnt lgkmcnt(0)
	v_mfma_f32_32x32x16_bf16 v[0:15], v[204:207], v[16:19], v[0:15]
	v_lshl_add_u64 v[16:17], v[24:25], 0, s[2:3]
	s_cselect_b64 s[2:3], -1, 0
	s_and_b64 s[2:3], s[2:3], vcc
	s_nop 8
	v_cvt_pk_bf16_f32 v0, v0, v1
	v_cvt_pk_bf16_f32 v1, v2, v3
	v_cvt_pk_bf16_f32 v2, v4, v5
	v_cvt_pk_bf16_f32 v3, v6, v7
	v_cvt_pk_bf16_f32 v4, v8, v9
	v_cvt_pk_bf16_f32 v5, v10, v11
	v_cvt_pk_bf16_f32 v6, v12, v13
	v_cvt_pk_bf16_f32 v7, v14, v15
	v_mbcnt_lo_u32_b32 v8, -1, 0
	v_mbcnt_hi_u32_b32 v8, -1, v8
	v_lshrrev_b32_e32 v8, 2, v8
	v_and_b32_e32 v8, 8, v8
	v_mov_b32_e32 v9, 0
	v_permlane32_swap_b32_e32 v0, v2
	v_permlane32_swap_b32_e32 v1, v3
	v_permlane32_swap_b32_e32 v4, v6
	v_permlane32_swap_b32_e32 v5, v7
	v_lshl_add_u64 v[16:17], v[16:17], 0, v[8:9]
	global_store_dwordx4 v[16:17], v[0:3], off
	global_store_dwordx4 v[16:17], v[4:7], off offset:32
	s_nop 1
	s_and_saveexec_b64 s[4:5], s[2:3]
	s_cbranch_execz .LBB0_958
	v_and_b32_e32 v0, 64, v211
	v_mul_u32_u24_e32 v0, 0x110, v0
	v_mul_u32_u24_e32 v1, 0x110, v208
	v_add3_u32 v16, s33, v0, v1
	ds_read_b128 v[0:3], v16
	ds_read_b128 v[4:7], v16 offset:16
	ds_read_b128 v[8:11], v16 offset:32
	ds_read_b128 v[12:15], v16 offset:48
	v_cmp_gt_u32_e32 vcc, 64, v209
	s_waitcnt lgkmcnt(3)
	v_lshlrev_b32_e32 v17, 16, v0
	v_and_b32_e32 v0, 0xffff0000, v0
	v_add_f32_e32 v17, 0, v17
	v_lshlrev_b32_e32 v18, 16, v1
	v_add_f32_e32 v0, v17, v0
	v_and_b32_e32 v1, 0xffff0000, v1
	v_add_f32_e32 v0, v0, v18
	v_lshlrev_b32_e32 v19, 16, v2
	v_add_f32_e32 v0, v0, v1
	v_and_b32_e32 v2, 0xffff0000, v2
	v_add_f32_e32 v0, v0, v19
	v_lshlrev_b32_e32 v20, 16, v3
	v_add_f32_e32 v0, v0, v2
	v_and_b32_e32 v3, 0xffff0000, v3
	v_add_f32_e32 v0, v0, v20
	v_add_f32_e32 v0, v0, v3
	s_waitcnt lgkmcnt(2)
	v_lshlrev_b32_e32 v1, 16, v4
	v_and_b32_e32 v2, 0xffff0000, v4
	v_add_f32_e32 v0, v0, v1
	v_lshlrev_b32_e32 v3, 16, v5
	v_add_f32_e32 v0, v0, v2
	v_and_b32_e32 v4, 0xffff0000, v5
	v_add_f32_e32 v0, v0, v3
	v_lshlrev_b32_e32 v5, 16, v6
	v_add_f32_e32 v0, v0, v4
	v_and_b32_e32 v6, 0xffff0000, v6
	v_add_f32_e32 v0, v0, v5
	v_lshlrev_b32_e32 v17, 16, v7
	v_add_f32_e32 v0, v0, v6
	v_and_b32_e32 v7, 0xffff0000, v7
	v_add_f32_e32 v0, v0, v17
	v_add_f32_e32 v0, v0, v7
	s_waitcnt lgkmcnt(1)
	v_lshlrev_b32_e32 v1, 16, v8
	v_and_b32_e32 v2, 0xffff0000, v8
	v_add_f32_e32 v0, v0, v1
	v_lshlrev_b32_e32 v3, 16, v9
	v_add_f32_e32 v0, v0, v2
	v_and_b32_e32 v4, 0xffff0000, v9
	v_add_f32_e32 v0, v0, v3
	v_lshlrev_b32_e32 v5, 16, v10
	v_add_f32_e32 v0, v0, v4
	v_and_b32_e32 v6, 0xffff0000, v10
	v_add_f32_e32 v0, v0, v5
	v_lshlrev_b32_e32 v7, 16, v11
	v_add_f32_e32 v0, v0, v6
	v_and_b32_e32 v8, 0xffff0000, v11
	v_add_f32_e32 v0, v0, v7
	v_add_f32_e32 v0, v0, v8
	s_waitcnt lgkmcnt(0)
	v_lshlrev_b32_e32 v1, 16, v12
	v_and_b32_e32 v2, 0xffff0000, v12
	v_add_f32_e32 v0, v0, v1
	v_lshlrev_b32_e32 v3, 16, v13
	v_add_f32_e32 v0, v0, v2
	v_and_b32_e32 v4, 0xffff0000, v13
	v_add_f32_e32 v0, v0, v3
	v_lshlrev_b32_e32 v5, 16, v14
	v_add_f32_e32 v0, v0, v4
	v_add_f32_e32 v4, v0, v5
	ds_read_b128 v[0:3], v16 offset:64
	v_and_b32_e32 v6, 0xffff0000, v14
	v_lshlrev_b32_e32 v7, 16, v15
	v_add_f32_e32 v4, v4, v6
	v_and_b32_e32 v8, 0xffff0000, v15
	v_add_f32_e32 v4, v4, v7
	v_add_f32_e32 v8, v4, v8
	ds_read_b128 v[4:7], v16 offset:80
	s_waitcnt lgkmcnt(1)
	v_lshlrev_b32_e32 v9, 16, v0
	v_and_b32_e32 v0, 0xffff0000, v0
	v_add_f32_e32 v8, v8, v9
	v_lshlrev_b32_e32 v10, 16, v1
	v_add_f32_e32 v0, v8, v0
	v_and_b32_e32 v1, 0xffff0000, v1
	v_add_f32_e32 v0, v0, v10
	v_lshlrev_b32_e32 v11, 16, v2
	v_add_f32_e32 v0, v0, v1
	v_and_b32_e32 v2, 0xffff0000, v2
	v_add_f32_e32 v0, v0, v11
	v_lshlrev_b32_e32 v12, 16, v3
	v_add_f32_e32 v0, v0, v2
	v_and_b32_e32 v3, 0xffff0000, v3
	v_add_f32_e32 v0, v0, v12
	v_add_f32_e32 v0, v0, v3
	s_waitcnt lgkmcnt(0)
	v_lshlrev_b32_e32 v1, 16, v4
	v_and_b32_e32 v2, 0xffff0000, v4
	v_add_f32_e32 v0, v0, v1
	v_lshlrev_b32_e32 v3, 16, v5
	v_add_f32_e32 v0, v0, v2
	v_and_b32_e32 v4, 0xffff0000, v5
	v_add_f32_e32 v0, v0, v3
	v_lshlrev_b32_e32 v5, 16, v6
	v_add_f32_e32 v0, v0, v4
	v_add_f32_e32 v4, v0, v5
	ds_read_b128 v[0:3], v16 offset:96
	v_and_b32_e32 v6, 0xffff0000, v6
	v_lshlrev_b32_e32 v8, 16, v7
	v_add_f32_e32 v4, v4, v6
	v_and_b32_e32 v7, 0xffff0000, v7
	v_add_f32_e32 v4, v4, v8
	v_add_f32_e32 v8, v4, v7
	ds_read_b128 v[4:7], v16 offset:112
	s_waitcnt lgkmcnt(1)
	v_lshlrev_b32_e32 v9, 16, v0
	v_and_b32_e32 v0, 0xffff0000, v0
	v_add_f32_e32 v8, v8, v9
	v_lshlrev_b32_e32 v10, 16, v1
	v_add_f32_e32 v0, v8, v0
	v_and_b32_e32 v1, 0xffff0000, v1
	v_add_f32_e32 v0, v0, v10
	v_lshlrev_b32_e32 v11, 16, v2
	v_add_f32_e32 v0, v0, v1
	v_and_b32_e32 v2, 0xffff0000, v2
	v_add_f32_e32 v0, v0, v11
	v_lshlrev_b32_e32 v12, 16, v3
	v_add_f32_e32 v0, v0, v2
	v_and_b32_e32 v3, 0xffff0000, v3
	v_add_f32_e32 v0, v0, v12
	v_add_f32_e32 v0, v0, v3
	s_waitcnt lgkmcnt(0)
	v_lshlrev_b32_e32 v1, 16, v4
	v_and_b32_e32 v2, 0xffff0000, v4
	v_add_f32_e32 v0, v0, v1
	v_lshlrev_b32_e32 v3, 16, v5
	v_add_f32_e32 v0, v0, v2
	v_and_b32_e32 v4, 0xffff0000, v5
	v_add_f32_e32 v0, v0, v3
	v_lshlrev_b32_e32 v5, 16, v6
	v_add_f32_e32 v0, v0, v4
	v_add_f32_e32 v4, v0, v5
	ds_read_b128 v[0:3], v16 offset:128
	v_and_b32_e32 v6, 0xffff0000, v6
	v_lshlrev_b32_e32 v8, 16, v7
	v_add_f32_e32 v4, v4, v6
	v_and_b32_e32 v7, 0xffff0000, v7
	v_add_f32_e32 v4, v4, v8
	v_add_f32_e32 v8, v4, v7
	ds_read_b128 v[4:7], v16 offset:144
	s_waitcnt lgkmcnt(1)
	v_lshlrev_b32_e32 v9, 16, v0
	v_and_b32_e32 v0, 0xffff0000, v0
	v_add_f32_e32 v8, v8, v9
	v_lshlrev_b32_e32 v10, 16, v1
	v_add_f32_e32 v0, v8, v0
	v_and_b32_e32 v1, 0xffff0000, v1
	v_add_f32_e32 v0, v0, v10
	v_lshlrev_b32_e32 v11, 16, v2
	v_add_f32_e32 v0, v0, v1
	v_and_b32_e32 v2, 0xffff0000, v2
	v_add_f32_e32 v0, v0, v11
	v_lshlrev_b32_e32 v12, 16, v3
	v_add_f32_e32 v0, v0, v2
	v_and_b32_e32 v3, 0xffff0000, v3
	v_add_f32_e32 v0, v0, v12
	v_add_f32_e32 v0, v0, v3
	s_waitcnt lgkmcnt(0)
	v_lshlrev_b32_e32 v1, 16, v4
	v_and_b32_e32 v2, 0xffff0000, v4
	v_add_f32_e32 v0, v0, v1
	v_lshlrev_b32_e32 v3, 16, v5
	v_add_f32_e32 v0, v0, v2
	v_and_b32_e32 v4, 0xffff0000, v5
	v_add_f32_e32 v0, v0, v3
	v_lshlrev_b32_e32 v5, 16, v6
	v_add_f32_e32 v0, v0, v4
	v_add_f32_e32 v4, v0, v5
	ds_read_b128 v[0:3], v16 offset:160
	v_and_b32_e32 v6, 0xffff0000, v6
	v_lshlrev_b32_e32 v8, 16, v7
	v_add_f32_e32 v4, v4, v6
	v_and_b32_e32 v7, 0xffff0000, v7
	v_add_f32_e32 v4, v4, v8
	v_add_f32_e32 v8, v4, v7
	ds_read_b128 v[4:7], v16 offset:176
	s_waitcnt lgkmcnt(1)
	v_lshlrev_b32_e32 v9, 16, v0
	v_and_b32_e32 v0, 0xffff0000, v0
	v_add_f32_e32 v8, v8, v9
	v_lshlrev_b32_e32 v10, 16, v1
	v_add_f32_e32 v0, v8, v0
	v_and_b32_e32 v1, 0xffff0000, v1
	v_add_f32_e32 v0, v0, v10
	v_lshlrev_b32_e32 v11, 16, v2
	v_add_f32_e32 v0, v0, v1
	v_and_b32_e32 v2, 0xffff0000, v2
	v_add_f32_e32 v0, v0, v11
	v_lshlrev_b32_e32 v12, 16, v3
	v_add_f32_e32 v0, v0, v2
	v_and_b32_e32 v3, 0xffff0000, v3
	v_add_f32_e32 v0, v0, v12
	v_add_f32_e32 v0, v0, v3
	s_waitcnt lgkmcnt(0)
	v_lshlrev_b32_e32 v1, 16, v4
	v_and_b32_e32 v2, 0xffff0000, v4
	v_add_f32_e32 v0, v0, v1
	v_lshlrev_b32_e32 v3, 16, v5
	v_add_f32_e32 v0, v0, v2
	v_and_b32_e32 v4, 0xffff0000, v5
	v_add_f32_e32 v0, v0, v3
	v_lshlrev_b32_e32 v5, 16, v6
	v_add_f32_e32 v0, v0, v4
	v_add_f32_e32 v4, v0, v5
	ds_read_b128 v[0:3], v16 offset:192
	v_and_b32_e32 v6, 0xffff0000, v6
	v_lshlrev_b32_e32 v8, 16, v7
	v_add_f32_e32 v4, v4, v6
	v_and_b32_e32 v7, 0xffff0000, v7
	v_add_f32_e32 v4, v4, v8
	v_add_f32_e32 v8, v4, v7
	ds_read_b128 v[4:7], v16 offset:208
	s_waitcnt lgkmcnt(1)
	v_lshlrev_b32_e32 v9, 16, v0
	v_and_b32_e32 v0, 0xffff0000, v0
	v_add_f32_e32 v8, v8, v9
	v_lshlrev_b32_e32 v10, 16, v1
	v_add_f32_e32 v0, v8, v0
	v_and_b32_e32 v1, 0xffff0000, v1
	v_add_f32_e32 v0, v0, v10
	v_lshlrev_b32_e32 v11, 16, v2
	v_add_f32_e32 v0, v0, v1
	v_and_b32_e32 v2, 0xffff0000, v2
	v_add_f32_e32 v0, v0, v11
	v_lshlrev_b32_e32 v12, 16, v3
	v_add_f32_e32 v0, v0, v2
	v_and_b32_e32 v3, 0xffff0000, v3
	v_add_f32_e32 v0, v0, v12
	v_add_f32_e32 v0, v0, v3
	s_waitcnt lgkmcnt(0)
	v_lshlrev_b32_e32 v1, 16, v4
	v_and_b32_e32 v2, 0xffff0000, v4
	v_add_f32_e32 v0, v0, v1
	v_lshlrev_b32_e32 v3, 16, v5
	v_add_f32_e32 v0, v0, v2
	v_and_b32_e32 v4, 0xffff0000, v5
	v_add_f32_e32 v0, v0, v3
	v_lshlrev_b32_e32 v5, 16, v6
	v_add_f32_e32 v0, v0, v4
	v_add_f32_e32 v4, v0, v5
	ds_read_b128 v[0:3], v16 offset:224
	v_and_b32_e32 v6, 0xffff0000, v6
	v_lshlrev_b32_e32 v8, 16, v7
	v_add_f32_e32 v4, v4, v6
	v_and_b32_e32 v7, 0xffff0000, v7
	v_add_f32_e32 v4, v4, v8
	v_add_f32_e32 v8, v4, v7
	ds_read_b128 v[4:7], v16 offset:240
	s_waitcnt lgkmcnt(1)
	v_lshlrev_b32_e32 v9, 16, v0
	v_and_b32_e32 v0, 0xffff0000, v0
	v_add_f32_e32 v8, v8, v9
	v_lshlrev_b32_e32 v10, 16, v1
	v_add_f32_e32 v0, v8, v0
	v_and_b32_e32 v1, 0xffff0000, v1
	v_add_f32_e32 v0, v0, v10
	v_lshlrev_b32_e32 v11, 16, v2
	v_add_f32_e32 v0, v0, v1
	v_and_b32_e32 v2, 0xffff0000, v2
	v_add_f32_e32 v0, v0, v11
	v_lshlrev_b32_e32 v12, 16, v3
	v_add_f32_e32 v0, v0, v2
	v_and_b32_e32 v3, 0xffff0000, v3
	v_add_f32_e32 v0, v0, v12
	v_add_f32_e32 v0, v0, v3
	s_waitcnt lgkmcnt(0)
	v_lshlrev_b32_e32 v1, 16, v4
	v_and_b32_e32 v2, 0xffff0000, v4
	v_add_f32_e32 v0, v0, v1
	v_lshlrev_b32_e32 v3, 16, v5
	v_add_f32_e32 v0, v0, v2
	v_and_b32_e32 v4, 0xffff0000, v5
	v_add_f32_e32 v0, v0, v3
	v_lshlrev_b32_e32 v5, 16, v6
	v_add_f32_e32 v0, v0, v4
	v_and_b32_e32 v6, 0xffff0000, v6
	v_add_f32_e32 v0, v0, v5
	v_lshlrev_b32_e32 v8, 16, v7
	v_add_f32_e32 v0, v0, v6
	v_and_b32_e32 v7, 0xffff0000, v7
	v_add_f32_e32 v0, v0, v8
	v_lshlrev_b32_e32 v2, 1, v210
	v_add_f32_e32 v3, v0, v7
	v_add3_u32 v0, s36, 4, v2
	v_lshl_or_b32 v4, v0, 3, s37
	v_mov_b32_e32 v0, s0
	v_mov_b32_e32 v1, s35
	v_cndmask_b32_e32 v0, v0, v1, vcc
	v_ashrrev_i32_e32 v1, 31, v0
	v_mad_i64_i32 v[0:1], s[0:1], v4, s90, v[0:1]
	v_lshlrev_b64 v[4:5], 8, v[0:1]
	v_lshl_add_u64 v[4:5], s[22:23], 0, v[4:5]
	v_lshlrev_b32_e32 v160, 2, v208
	v_lshl_add_u64 v[4:5], v[4:5], 0, v[160:161]
	v_cmp_eq_u32_e32 vcc, 0, v208
	global_store_dword v[4:5], v3, off
	s_and_b64 exec, exec, vcc
	s_cbranch_execz .LBB0_958
	v_lshl_add_u32 v2, v2, 2, s33
	ds_read_b64 v[2:3], v2 offset:53248
	v_lshl_add_u64 v[0:1], v[0:1], 3, s[24:25]
	s_waitcnt lgkmcnt(0)
	v_add_f32_e32 v4, v2, v3
	v_mov_b32_e32 v5, v2
	global_store_dwordx2 v[0:1], v[4:5], off
	s_branch .LBB0_958
